# GEMM K-loop: only five fragment reads ahead of the first MFMAs, the rest interleaved with counted lgkmcnt
# baseline (speedup 1.0000x reference)
.LBB0_246:
	s_add_i32 s10, s7, 0xffffa000
	s_cmp_lg_u32 s7, 0
	s_cselect_b32 s12, s10, 0xc000
	v_add_u32_e32 v131, s7, v150
	s_waitcnt vmcnt(6)
	s_barrier
	v_add_u32_e32 v133, s7, v149
	ds_read_b128 v[154:157], v131 offset:0
	v_add_u32_e32 v153, s12, v147
	ds_read_b128 v[170:173], v133 offset:0
	ds_read_b128 v[174:177], v133 offset:0x400
	ds_read_b128 v[178:181], v133 offset:0x800
	ds_read_b128 v[200:203], v133 offset:0xc00
	s_add_u32 s10, s8, s50
	s_addc_u32 s11, s9, s51
	v_readfirstlane_b32 s13, v153
	s_add_u32 s64, s5, s100
	s_addc_u32 s65, s6, 0
	s_sub_i32 s68, s13, s12
	s_lshr_b32 s68, s68, 1
	s_add_i32 s68, s68, s12
	s_addk_i32 s68, 0x4000
	s_waitcnt lgkmcnt(0)
	s_nop 0
	v_mfma_f32_16x16x32_bf16 v[126:129], v[154:157], v[170:173], v[126:129]
	ds_read_b128 v[158:161], v131 offset:0x400
	v_mfma_f32_16x16x32_bf16 v[122:125], v[154:157], v[174:177], v[122:125]
	ds_read_b128 v[162:165], v131 offset:0x800
	v_mfma_f32_16x16x32_bf16 v[118:121], v[154:157], v[178:181], v[118:121]
	ds_read_b128 v[166:169], v131 offset:0xc00
	v_mfma_f32_16x16x32_bf16 v[114:117], v[154:157], v[200:203], v[114:117]
	ds_read_b128 v[204:207], v133 offset:0x1000
	s_waitcnt lgkmcnt(3)
	v_mfma_f32_16x16x32_bf16 v[110:113], v[158:161], v[170:173], v[110:113]
	ds_read_b128 v[208:211], v133 offset:0x1400
	s_mov_b32 m0, s13
	s_nop 0
	global_load_lds_dwordx4 v0, s[10:11]
	v_mfma_f32_16x16x32_bf16 v[102:105], v[158:161], v[174:177], v[102:105]
	ds_read_b128 v[212:215], v133 offset:0x1800
	v_mfma_f32_16x16x32_bf16 v[94:97], v[158:161], v[178:181], v[94:97]
	ds_read_b128 v[216:219], v133 offset:0x1c00
	v_mfma_f32_16x16x32_bf16 v[86:89], v[158:161], v[200:203], v[86:89]
	s_add_u32 m0, s13, 0x400
	s_nop 0
	global_load_lds_dwordx4 v130, s[10:11]
	s_waitcnt lgkmcnt(5)
	v_mfma_f32_16x16x32_bf16 v[78:81], v[162:165], v[170:173], v[78:81]
	v_mfma_f32_16x16x32_bf16 v[70:73], v[162:165], v[174:177], v[70:73]
	v_mfma_f32_16x16x32_bf16 v[62:65], v[162:165], v[178:181], v[62:65]
	s_add_u32 m0, s13, 0x800
	s_nop 0
	global_load_lds_dwordx4 v132, s[10:11]
	v_mfma_f32_16x16x32_bf16 v[54:57], v[162:165], v[200:203], v[54:57]
	s_waitcnt lgkmcnt(4)
	v_mfma_f32_16x16x32_bf16 v[46:49], v[166:169], v[170:173], v[46:49]
	v_mfma_f32_16x16x32_bf16 v[38:41], v[166:169], v[174:177], v[38:41]
	s_add_u32 m0, s13, 0xc00
	s_nop 0
	global_load_lds_dwordx4 v136, s[10:11]
	v_mfma_f32_16x16x32_bf16 v[30:33], v[166:169], v[178:181], v[30:33]
	v_mfma_f32_16x16x32_bf16 v[22:25], v[166:169], v[200:203], v[22:25]
	s_mov_b32 m0, s68
	s_nop 0
	global_load_lds_dwordx4 v138, s[64:65]
	s_waitcnt lgkmcnt(0)
	s_nop 0
	v_mfma_f32_16x16x32_bf16 v[106:109], v[154:157], v[204:207], v[106:109]
	v_mfma_f32_16x16x32_bf16 v[98:101], v[154:157], v[208:211], v[98:101]
	v_mfma_f32_16x16x32_bf16 v[90:93], v[154:157], v[212:215], v[90:93]
	v_mfma_f32_16x16x32_bf16 v[82:85], v[154:157], v[216:219], v[82:85]
	v_mfma_f32_16x16x32_bf16 v[74:77], v[158:161], v[204:207], v[74:77]
	v_mfma_f32_16x16x32_bf16 v[66:69], v[158:161], v[208:211], v[66:69]
	s_add_u32 m0, s68, 0x400
	s_nop 0
	global_load_lds_dwordx4 v140, s[64:65]
	v_mfma_f32_16x16x32_bf16 v[58:61], v[158:161], v[212:215], v[58:61]
	v_mfma_f32_16x16x32_bf16 v[50:53], v[158:161], v[216:219], v[50:53]
	v_mfma_f32_16x16x32_bf16 v[42:45], v[162:165], v[204:207], v[42:45]
	v_mfma_f32_16x16x32_bf16 v[34:37], v[162:165], v[208:211], v[34:37]
	v_mfma_f32_16x16x32_bf16 v[26:29], v[162:165], v[212:215], v[26:29]
	v_mfma_f32_16x16x32_bf16 v[18:21], v[162:165], v[216:219], v[18:21]
	v_mfma_f32_16x16x32_bf16 v[14:17], v[166:169], v[204:207], v[14:17]
	v_mfma_f32_16x16x32_bf16 v[10:13], v[166:169], v[208:211], v[10:13]
	v_mfma_f32_16x16x32_bf16 v[6:9], v[166:169], v[212:215], v[6:9]
	v_mfma_f32_16x16x32_bf16 v[2:5], v[166:169], v[216:219], v[2:5]
	s_add_i32 s10, s7, 0x6000
	s_cmpk_lg_u32 s7, 0xc000
	s_cselect_b32 s7, s10, 0
	s_addk_i32 s100, 0x400
	s_add_u32 s50, s50, s60
	s_addc_u32 s51, s51, 0
	s_cmpk_lg_i32 s100, 0x7800
	s_cbranch_scc1 .LBB0_246
	s_waitcnt vmcnt(6)
	s_barrier
	v_add_u32_e32 v0, s7, v150
	v_add_u32_e32 v140, s7, v149
	ds_read_b128 v[130:133], v0 offset:0
	ds_read_b128 v[136:139], v0 offset:0x400
	ds_read_b128 v[154:157], v0 offset:0x800
	ds_read_b128 v[158:161], v0 offset:0xc00
	ds_read_b128 v[162:165], v140 offset:0
	ds_read_b128 v[166:169], v140 offset:0x400
	ds_read_b128 v[170:173], v140 offset:0x800
	ds_read_b128 v[174:177], v140 offset:0xc00
	ds_read_b128 v[178:181], v140 offset:0x1000
	ds_read_b128 v[200:203], v140 offset:0x1400
	ds_read_b128 v[204:207], v140 offset:0x1800
	ds_read_b128 v[208:211], v140 offset:0x1c00
	s_lshl_b32 s49, s4, 8
	s_waitcnt lgkmcnt(4)
	s_nop 0
	v_mfma_f32_16x16x32_bf16 v[126:129], v[130:133], v[162:165], v[126:129]
	v_mfma_f32_16x16x32_bf16 v[118:121], v[130:133], v[170:173], v[118:121]
	v_mfma_f32_16x16x32_bf16 v[114:117], v[130:133], v[174:177], v[114:117]
	v_mfma_f32_16x16x32_bf16 v[110:113], v[136:139], v[162:165], v[110:113]
	v_mfma_f32_16x16x32_bf16 v[102:105], v[136:139], v[166:169], v[102:105]
	v_mfma_f32_16x16x32_bf16 v[94:97], v[136:139], v[170:173], v[94:97]
	v_mfma_f32_16x16x32_bf16 v[86:89], v[136:139], v[174:177], v[86:89]
	v_mfma_f32_16x16x32_bf16 v[70:73], v[154:157], v[166:169], v[70:73]
	v_mfma_f32_16x16x32_bf16 v[62:65], v[154:157], v[170:173], v[62:65]
	v_mfma_f32_16x16x32_bf16 v[54:57], v[154:157], v[174:177], v[54:57]
	v_mfma_f32_16x16x32_bf16 v[46:49], v[158:161], v[162:165], v[46:49]
	v_mfma_f32_16x16x32_bf16 v[38:41], v[158:161], v[166:169], v[38:41]
	v_mfma_f32_16x16x32_bf16 v[30:33], v[158:161], v[170:173], v[30:33]
	v_mfma_f32_16x16x32_bf16 v[22:25], v[158:161], v[174:177], v[22:25]
	v_mfma_f32_16x16x32_bf16 v[212:215], v[130:133], v[166:169], v[122:125]
	v_mfma_f32_16x16x32_bf16 v[216:219], v[154:157], v[162:165], v[78:81]
	s_waitcnt lgkmcnt(0)
	s_nop 0
	v_mfma_f32_16x16x32_bf16 v[174:177], v[136:139], v[178:181], v[74:77]
	v_mfma_f32_16x16x32_bf16 v[220:223], v[136:139], v[200:203], v[66:69]
	v_mfma_f32_16x16x32_bf16 v[224:227], v[136:139], v[204:207], v[58:61]
	v_mfma_f32_16x16x32_bf16 v[50:53], v[136:139], v[208:211], v[50:53]
	v_mfma_f32_16x16x32_bf16 v[136:139], v[154:157], v[178:181], v[42:45]
	v_mfma_f32_16x16x32_bf16 v[34:37], v[154:157], v[200:203], v[34:37]
	v_mfma_f32_16x16x32_bf16 v[6:9], v[158:161], v[204:207], v[6:9]
	v_mfma_f32_16x16x32_bf16 v[162:165], v[130:133], v[178:181], v[106:109]
	v_mfma_f32_16x16x32_bf16 v[166:169], v[130:133], v[200:203], v[98:101]
	v_mfma_f32_16x16x32_bf16 v[170:173], v[130:133], v[204:207], v[90:93]
	v_mfma_f32_16x16x32_bf16 v[130:133], v[130:133], v[208:211], v[82:85]
	v_mfma_f32_16x16x32_bf16 v[228:231], v[154:157], v[204:207], v[26:29]
	v_mfma_f32_16x16x32_bf16 v[154:157], v[154:157], v[208:211], v[18:21]
	v_mfma_f32_16x16x32_bf16 v[178:181], v[158:161], v[178:181], v[14:17]
	v_mfma_f32_16x16x32_bf16 v[200:203], v[158:161], v[200:203], v[10:13]
	v_mfma_f32_16x16x32_bf16 v[158:161], v[158:161], v[208:211], v[2:5]
	s_waitcnt vmcnt(0)
	s_barrier
	ds_read_b128 v[2:5], v151 offset:0
	ds_read_b128 v[14:17], v151 offset:0x400
	ds_read_b128 v[204:207], v151 offset:0x800
	ds_read_b128 v[208:211], v151 offset:0xc00
	ds_read_b128 v[10:13], v152 offset:0
	ds_read_b128 v[18:21], v152 offset:0x400
	ds_read_b128 v[26:29], v152 offset:0x800
	ds_read_b128 v[42:45], v152 offset:0xc00
	ds_read_b128 v[232:235], v152 offset:0x1000
	ds_read_b128 v[236:239], v152 offset:0x1400
	ds_read_b128 v[240:243], v152 offset:0x1800
	ds_read_b128 v[244:247], v152 offset:0x1c00
	s_nop 0
	s_waitcnt lgkmcnt(4)
	s_nop 0
	v_mfma_f32_16x16x32_bf16 v[122:125], v[2:5], v[10:13], v[126:129]
	v_mfma_f32_16x16x32_bf16 v[106:109], v[2:5], v[18:21], v[212:215]
	v_mfma_f32_16x16x32_bf16 v[90:93], v[2:5], v[26:29], v[118:121]
	v_mfma_f32_16x16x32_bf16 v[74:77], v[2:5], v[42:45], v[114:117]
	v_mfma_f32_16x16x32_bf16 v[126:129], v[14:17], v[10:13], v[110:113]
	v_mfma_f32_16x16x32_bf16 v[110:113], v[14:17], v[18:21], v[102:105]
	v_mfma_f32_16x16x32_bf16 v[94:97], v[14:17], v[26:29], v[94:97]
	v_mfma_f32_16x16x32_bf16 v[78:81], v[14:17], v[42:45], v[86:89]
	v_mfma_f32_16x16x32_bf16 v[114:117], v[204:207], v[10:13], v[216:219]
	v_mfma_f32_16x16x32_bf16 v[98:101], v[204:207], v[18:21], v[70:73]
	v_mfma_f32_16x16x32_bf16 v[82:85], v[204:207], v[26:29], v[62:65]
	v_mfma_f32_16x16x32_bf16 v[66:69], v[204:207], v[42:45], v[54:57]
	v_mfma_f32_16x16x32_bf16 v[118:121], v[208:211], v[10:13], v[46:49]
	v_mfma_f32_16x16x32_bf16 v[102:105], v[208:211], v[18:21], v[38:41]
	v_mfma_f32_16x16x32_bf16 v[86:89], v[208:211], v[26:29], v[30:33]
	v_mfma_f32_16x16x32_bf16 v[70:73], v[208:211], v[42:45], v[22:25]
	s_waitcnt lgkmcnt(0)
	s_nop 0
	v_mfma_f32_16x16x32_bf16 v[58:61], v[2:5], v[232:235], v[162:165]
	v_mfma_f32_16x16x32_bf16 v[42:45], v[2:5], v[236:239], v[166:169]
	v_mfma_f32_16x16x32_bf16 v[26:29], v[2:5], v[240:243], v[170:173]
	v_mfma_f32_16x16x32_bf16 v[10:13], v[2:5], v[244:247], v[130:133]
	v_mfma_f32_16x16x32_bf16 v[62:65], v[14:17], v[232:235], v[174:177]
	v_mfma_f32_16x16x32_bf16 v[46:49], v[14:17], v[236:239], v[220:223]
	v_mfma_f32_16x16x32_bf16 v[30:33], v[14:17], v[240:243], v[224:227]
	v_mfma_f32_16x16x32_bf16 v[14:17], v[14:17], v[244:247], v[50:53]
	v_mfma_f32_16x16x32_bf16 v[50:53], v[204:207], v[232:235], v[136:139]
	v_mfma_f32_16x16x32_bf16 v[34:37], v[204:207], v[236:239], v[34:37]
	v_mfma_f32_16x16x32_bf16 v[18:21], v[204:207], v[240:243], v[228:231]
	v_mfma_f32_16x16x32_bf16 v[2:5], v[204:207], v[244:247], v[154:157]
	v_mfma_f32_16x16x32_bf16 v[54:57], v[208:211], v[232:235], v[178:181]
	v_mfma_f32_16x16x32_bf16 v[38:41], v[208:211], v[236:239], v[200:203]
	v_mfma_f32_16x16x32_bf16 v[22:25], v[208:211], v[240:243], v[6:9]
	v_mfma_f32_16x16x32_bf16 v[6:9], v[208:211], v[244:247], v[158:161]
	v_mov_b32_e32 v136, v134
	s_mov_b64 s[50:51], -1
	s_and_b64 vcc, exec, s[22:23]
	s_barrier
	s_cbranch_vccz .LBB0_264
	s_and_b64 vcc, exec, s[0:1]
	s_cbranch_vccz .LBB0_250
	v_lshrrev_b32_e32 v0, 6, v136
	v_mul_lo_u32 v137, v0, s14
	v_and_b32_e32 v130, 15, v136
	v_and_or_b32 v0, v136, 48, v137
	s_movk_i32 s4, 0x90
	v_mad_u32_u24 v0, v130, s4, v0
	v_cvt_pk_bf16_f32 v130, v122, v123
	v_cvt_pk_bf16_f32 v131, v124, v125
	v_cvt_pk_bf16_f32 v132, v126, v127
	v_cvt_pk_bf16_f32 v133, v128, v129
	s_waitcnt vmcnt(0)
	ds_write_b128 v0, v[130:133]
	v_cvt_pk_bf16_f32 v130, v114, v115
	v_cvt_pk_bf16_f32 v131, v116, v117
	v_cvt_pk_bf16_f32 v132, v118, v119
	v_cvt_pk_bf16_f32 v133, v120, v121
	ds_write_b128 v0, v[130:133] offset:64
	v_cvt_pk_bf16_f32 v130, v106, v107
	v_cvt_pk_bf16_f32 v131, v108, v109
	v_cvt_pk_bf16_f32 v132, v110, v111
	v_cvt_pk_bf16_f32 v133, v112, v113
	ds_write_b128 v0, v[130:133] offset:2304
	v_cvt_pk_bf16_f32 v130, v98, v99
	v_cvt_pk_bf16_f32 v131, v100, v101
	v_cvt_pk_bf16_f32 v132, v102, v103
	v_cvt_pk_bf16_f32 v133, v104, v105
	ds_write_b128 v0, v[130:133] offset:2368
	v_cvt_pk_bf16_f32 v130, v90, v91
	v_cvt_pk_bf16_f32 v131, v92, v93
	v_cvt_pk_bf16_f32 v132, v94, v95
	v_cvt_pk_bf16_f32 v133, v96, v97
	ds_write_b128 v0, v[130:133] offset:4608
	v_cvt_pk_bf16_f32 v130, v82, v83
	v_cvt_pk_bf16_f32 v131, v84, v85
	v_cvt_pk_bf16_f32 v132, v86, v87
	v_cvt_pk_bf16_f32 v133, v88, v89
	ds_write_b128 v0, v[130:133] offset:4672
	v_cvt_pk_bf16_f32 v130, v74, v75
	v_cvt_pk_bf16_f32 v131, v76, v77
	v_cvt_pk_bf16_f32 v132, v78, v79
	v_cvt_pk_bf16_f32 v133, v80, v81
	ds_write_b128 v0, v[130:133] offset:6912
	v_cvt_pk_bf16_f32 v130, v66, v67
	v_cvt_pk_bf16_f32 v131, v68, v69
	v_cvt_pk_bf16_f32 v132, v70, v71
	v_cvt_pk_bf16_f32 v133, v72, v73
	ds_write_b128 v0, v[130:133] offset:6976
	v_cvt_pk_bf16_f32 v130, v58, v59
	v_cvt_pk_bf16_f32 v131, v60, v61
	v_cvt_pk_bf16_f32 v132, v62, v63
	v_cvt_pk_bf16_f32 v133, v64, v65
	ds_write_b128 v0, v[130:133] offset:9216
	v_cvt_pk_bf16_f32 v130, v50, v51
	v_cvt_pk_bf16_f32 v131, v52, v53
	v_cvt_pk_bf16_f32 v132, v54, v55
	v_cvt_pk_bf16_f32 v133, v56, v57
	ds_write_b128 v0, v[130:133] offset:9280
	v_cvt_pk_bf16_f32 v130, v42, v43
	v_cvt_pk_bf16_f32 v131, v44, v45
	v_cvt_pk_bf16_f32 v132, v46, v47
	v_cvt_pk_bf16_f32 v133, v48, v49
	ds_write_b128 v0, v[130:133] offset:11520
	v_cvt_pk_bf16_f32 v130, v34, v35
	v_cvt_pk_bf16_f32 v131, v36, v37
	v_cvt_pk_bf16_f32 v132, v38, v39
	v_cvt_pk_bf16_f32 v133, v40, v41
	ds_write_b128 v0, v[130:133] offset:11584
	v_cvt_pk_bf16_f32 v130, v26, v27
	v_cvt_pk_bf16_f32 v131, v28, v29
	v_cvt_pk_bf16_f32 v132, v30, v31
	v_cvt_pk_bf16_f32 v133, v32, v33
	ds_write_b128 v0, v[130:133] offset:13824
	v_cvt_pk_bf16_f32 v130, v18, v19
	v_cvt_pk_bf16_f32 v131, v20, v21
	v_cvt_pk_bf16_f32 v132, v22, v23
	v_cvt_pk_bf16_f32 v133, v24, v25
	ds_write_b128 v0, v[130:133] offset:13888
	v_cvt_pk_bf16_f32 v130, v10, v11
	v_cvt_pk_bf16_f32 v131, v12, v13
	v_cvt_pk_bf16_f32 v132, v14, v15
	v_cvt_pk_bf16_f32 v133, v16, v17
	ds_write_b128 v0, v[130:133] offset:16128
	v_cvt_pk_bf16_f32 v130, v2, v3
	v_cvt_pk_bf16_f32 v131, v4, v5
	v_cvt_pk_bf16_f32 v132, v6, v7
	v_cvt_pk_bf16_f32 v133, v8, v9
	ds_write_b128 v0, v[130:133] offset:16192
	v_and_b32_e32 v0, 0xffffff80, v136
	v_add_u32_e32 v130, s48, v0
	v_ashrrev_i32_e32 v131, 31, v130
	v_lshlrev_b64 v[130:131], 11, v[130:131]
	v_lshl_add_u64 v[130:131], s[38:39], 0, v[130:131]
	v_and_b32_e32 v0, 64, v136
	v_lshl_add_u64 v[130:131], s[46:47], 1, v[130:131]
	v_lshlrev_b32_e32 v0, 1, v0
	v_lshl_add_u64 v[138:139], v[130:131], 0, v[0:1]
	v_lshlrev_b32_e32 v0, 4, v136
	v_and_b32_e32 v0, 0x70, v0
	v_bfe_u32 v140, v136, 3, 3
	v_or_b32_e32 v130, v137, v0
	s_waitcnt lgkmcnt(0)
	v_mad_u32_u24 v137, v140, s4, v130
	ds_read_b128 v[130:133], v137
	v_lshl_add_u64 v[138:139], v[138:139], 0, v[0:1]
	v_lshlrev_b32_e32 v0, 11, v140
	v_lshl_add_u64 v[140:141], v[138:139], 0, v[0:1]
	s_mov_b64 s[50:51], 0
	s_waitcnt lgkmcnt(0)
	global_store_dwordx4 v[140:141], v[130:133], off
	ds_read_b128 v[130:133], v137 offset:1152
	v_or_b32_e32 v140, 0x4000, v0
	v_mov_b32_e32 v141, v1
	v_lshl_add_u64 v[140:141], v[138:139], 0, v[140:141]
	s_waitcnt lgkmcnt(0)
	global_store_dwordx4 v[140:141], v[130:133], off
	ds_read_b128 v[130:133], v137 offset:2304
	v_or_b32_e32 v140, 0x8000, v0
	v_mov_b32_e32 v141, v1
	v_lshl_add_u64 v[140:141], v[138:139], 0, v[140:141]
	s_waitcnt lgkmcnt(0)
	global_store_dwordx4 v[140:141], v[130:133], off
	ds_read_b128 v[130:133], v137 offset:3456
	v_or_b32_e32 v140, 0xc000, v0
	v_mov_b32_e32 v141, v1
	v_lshl_add_u64 v[140:141], v[138:139], 0, v[140:141]
	s_waitcnt lgkmcnt(0)
	global_store_dwordx4 v[140:141], v[130:133], off
	ds_read_b128 v[130:133], v137 offset:4608
	v_or_b32_e32 v140, 0x10000, v0
	v_mov_b32_e32 v141, v1
	v_lshl_add_u64 v[140:141], v[138:139], 0, v[140:141]
	s_waitcnt lgkmcnt(0)
	global_store_dwordx4 v[140:141], v[130:133], off
	ds_read_b128 v[130:133], v137 offset:5760
	v_or_b32_e32 v140, 0x14000, v0
	v_mov_b32_e32 v141, v1
	v_lshl_add_u64 v[140:141], v[138:139], 0, v[140:141]
	s_waitcnt lgkmcnt(0)
	global_store_dwordx4 v[140:141], v[130:133], off
	ds_read_b128 v[130:133], v137 offset:6912
	v_or_b32_e32 v140, 0x18000, v0
	v_mov_b32_e32 v141, v1
	v_lshl_add_u64 v[140:141], v[138:139], 0, v[140:141]
	s_waitcnt lgkmcnt(0)
	global_store_dwordx4 v[140:141], v[130:133], off
	ds_read_b128 v[130:133], v137 offset:8064
	v_or_b32_e32 v140, 0x1c000, v0
	v_mov_b32_e32 v141, v1
	v_lshl_add_u64 v[140:141], v[138:139], 0, v[140:141]
	s_waitcnt lgkmcnt(0)
	global_store_dwordx4 v[140:141], v[130:133], off
	ds_read_b128 v[130:133], v137 offset:9216
	v_or_b32_e32 v140, 0x20000, v0
	v_mov_b32_e32 v141, v1
	v_lshl_add_u64 v[140:141], v[138:139], 0, v[140:141]
	s_waitcnt lgkmcnt(0)
	global_store_dwordx4 v[140:141], v[130:133], off
	ds_read_b128 v[130:133], v137 offset:10368
	v_or_b32_e32 v140, 0x24000, v0
	v_mov_b32_e32 v141, v1
	v_lshl_add_u64 v[140:141], v[138:139], 0, v[140:141]
	s_waitcnt lgkmcnt(0)
	global_store_dwordx4 v[140:141], v[130:133], off
	ds_read_b128 v[130:133], v137 offset:11520
	v_or_b32_e32 v140, 0x28000, v0
	v_mov_b32_e32 v141, v1
	v_lshl_add_u64 v[140:141], v[138:139], 0, v[140:141]
	s_waitcnt lgkmcnt(0)
	global_store_dwordx4 v[140:141], v[130:133], off
	ds_read_b128 v[130:133], v137 offset:12672
	v_or_b32_e32 v140, 0x2c000, v0
	v_mov_b32_e32 v141, v1
	v_lshl_add_u64 v[140:141], v[138:139], 0, v[140:141]
	s_waitcnt lgkmcnt(0)
	global_store_dwordx4 v[140:141], v[130:133], off
	ds_read_b128 v[130:133], v137 offset:13824
	v_or_b32_e32 v140, 0x30000, v0
	v_mov_b32_e32 v141, v1
	v_lshl_add_u64 v[140:141], v[138:139], 0, v[140:141]
	s_waitcnt lgkmcnt(0)
	global_store_dwordx4 v[140:141], v[130:133], off
	ds_read_b128 v[130:133], v137 offset:14976
	v_or_b32_e32 v140, 0x34000, v0
	v_mov_b32_e32 v141, v1
	v_lshl_add_u64 v[140:141], v[138:139], 0, v[140:141]
	s_waitcnt lgkmcnt(0)
	global_store_dwordx4 v[140:141], v[130:133], off
	ds_read_b128 v[130:133], v137 offset:16128
	v_or_b32_e32 v140, 0x38000, v0
	v_mov_b32_e32 v141, v1
	v_lshl_add_u64 v[140:141], v[138:139], 0, v[140:141]
	v_or_b32_e32 v0, 0x3c000, v0
	s_waitcnt lgkmcnt(0)
	global_store_dwordx4 v[140:141], v[130:133], off
	ds_read_b128 v[130:133], v137 offset:17280
	v_lshl_add_u64 v[138:139], v[138:139], 0, v[0:1]
	s_waitcnt lgkmcnt(0)
	global_store_dwordx4 v[138:139], v[130:133], off
	s_waitcnt lgkmcnt(0)
	s_barrier
